# GEMM K-loops: alternative MFMA order - each accumulator's two K-steps two instructions apart, neighbours sharing the A fragment; otherwise as v67 (compare with v68)
# baseline (speedup 1.0000x reference)
.LBB0_320:
	s_add_u32 s20, s40, 0xfffc0080
	s_addc_u32 s21, s41, -1
	s_add_i32 s77, 0, 0x10000
	s_cmp_eq_u32 s76, 12
	s_cselect_b32 s59, s49, s21
	s_cselect_b32 s58, s55, s20
	s_cselect_b32 s21, s45, s75
	s_cselect_b32 s20, s73, s74
	s_add_i32 s80, 0, 0x14000
	v_add_u32_e32 v60, s77, v183
	v_add_u32_e32 v168, s80, v183
	ds_read_b128 v[48:51], v60
	ds_read_b128 v[52:55], v60 offset:1024
	ds_read_b128 v[56:59], v60 offset:2048
	ds_read_b128 v[60:63], v60 offset:3072
	ds_read_b128 v[164:167], v168
	ds_read_b128 v[170:173], v168 offset:1024
	ds_read_b128 v[174:177], v168 offset:2048
	ds_read_b128 v[178:181], v168 offset:3072
	v_lshl_add_u64 v[228:229], s[40:41], 0, v[162:163]
	s_add_i32 m0, s57, 0xc000
	ds_read_b128 v[204:207], v202
	ds_read_b128 v[208:211], v202 offset:1024
	ds_read_b128 v[212:215], v202 offset:2048
	ds_read_b128 v[216:219], v202 offset:3072
	ds_read_b128 v[220:223], v202 offset:4096
	ds_read_b128 v[224:227], v202 offset:5120
	ds_read_b128 v[240:243], v202 offset:6144
	ds_read_b128 v[244:247], v202 offset:7168
	global_load_lds_dwordx4 v[228:229], off
	v_lshl_add_u64 v[228:229], s[40:41], 0, v[160:161]
	s_add_i32 m0, s57, 0xe000
	s_nop 0
	global_load_lds_dwordx4 v[228:229], off
	s_waitcnt vmcnt(8)
	s_waitcnt lgkmcnt(0)
	s_setprio 1
	s_barrier
	v_mfma_f32_16x16x32_bf16 v[140:143], v[48:51], v[204:207], v[140:143]
	v_mfma_f32_16x16x32_bf16 v[136:139], v[56:59], v[204:207], v[136:139]
	v_mfma_f32_16x16x32_bf16 v[140:143], v[52:55], v[208:211], v[140:143]
	v_mfma_f32_16x16x32_bf16 v[136:139], v[60:63], v[208:211], v[136:139]
	v_mfma_f32_16x16x32_bf16 v[124:127], v[48:51], v[212:215], v[124:127]
	v_mfma_f32_16x16x32_bf16 v[120:123], v[56:59], v[212:215], v[120:123]
	v_mfma_f32_16x16x32_bf16 v[124:127], v[52:55], v[216:219], v[124:127]
	v_mfma_f32_16x16x32_bf16 v[120:123], v[60:63], v[216:219], v[120:123]
	v_mfma_f32_16x16x32_bf16 v[108:111], v[48:51], v[220:223], v[108:111]
	v_mfma_f32_16x16x32_bf16 v[104:107], v[56:59], v[220:223], v[104:107]
	v_mfma_f32_16x16x32_bf16 v[108:111], v[52:55], v[224:227], v[108:111]
	v_mfma_f32_16x16x32_bf16 v[104:107], v[60:63], v[224:227], v[104:107]
	v_mfma_f32_16x16x32_bf16 v[92:95], v[48:51], v[240:243], v[92:95]
	v_mfma_f32_16x16x32_bf16 v[88:91], v[56:59], v[240:243], v[88:91]
	v_mfma_f32_16x16x32_bf16 v[92:95], v[52:55], v[244:247], v[92:95]
	v_mfma_f32_16x16x32_bf16 v[88:91], v[60:63], v[244:247], v[88:91]
	v_mfma_f32_16x16x32_bf16 v[132:135], v[164:167], v[204:207], v[132:135]
	v_mfma_f32_16x16x32_bf16 v[128:131], v[174:177], v[204:207], v[128:131]
	v_mfma_f32_16x16x32_bf16 v[132:135], v[170:173], v[208:211], v[132:135]
	v_mfma_f32_16x16x32_bf16 v[128:131], v[178:181], v[208:211], v[128:131]
	v_mfma_f32_16x16x32_bf16 v[116:119], v[164:167], v[212:215], v[116:119]
	v_mfma_f32_16x16x32_bf16 v[112:115], v[174:177], v[212:215], v[112:115]
	v_mfma_f32_16x16x32_bf16 v[116:119], v[170:173], v[216:219], v[116:119]
	v_mfma_f32_16x16x32_bf16 v[112:115], v[178:181], v[216:219], v[112:115]
	v_mfma_f32_16x16x32_bf16 v[100:103], v[164:167], v[220:223], v[100:103]
	v_mfma_f32_16x16x32_bf16 v[96:99], v[174:177], v[220:223], v[96:99]
	v_mfma_f32_16x16x32_bf16 v[100:103], v[170:173], v[224:227], v[100:103]
	v_mfma_f32_16x16x32_bf16 v[96:99], v[178:181], v[224:227], v[96:99]
	v_mfma_f32_16x16x32_bf16 v[84:87], v[164:167], v[240:243], v[84:87]
	v_mfma_f32_16x16x32_bf16 v[80:83], v[174:177], v[240:243], v[80:83]
	v_mfma_f32_16x16x32_bf16 v[84:87], v[170:173], v[244:247], v[84:87]
	v_mfma_f32_16x16x32_bf16 v[80:83], v[178:181], v[244:247], v[80:83]
	s_barrier
	s_setprio 0
	s_add_i32 s77, s77, s62
	v_lshl_add_u64 v[228:229], s[20:21], 0, v[146:147]
	s_mov_b32 m0, s77
	ds_read_b128 v[204:207], v202 offset:16384
	ds_read_b128 v[208:211], v202 offset:17408
	ds_read_b128 v[212:215], v202 offset:18432
	ds_read_b128 v[216:219], v202 offset:19456
	ds_read_b128 v[220:223], v202 offset:20480
	ds_read_b128 v[224:227], v202 offset:21504
	ds_read_b128 v[240:243], v202 offset:22528
	ds_read_b128 v[244:247], v202 offset:23552
	global_load_lds_dwordx4 v[228:229], off
	s_add_i32 m0, s77, 0x2000
	s_add_u32 s78, s20, 0x40000
	v_lshl_add_u64 v[230:231], s[20:21], 0, v[150:151]
	s_addc_u32 s79, s21, 0
	s_add_i32 s77, s80, s62
	global_load_lds_dwordx4 v[230:231], off
	v_lshl_add_u64 v[232:233], s[78:79], 0, v[146:147]
	s_mov_b32 m0, s77
	v_lshl_add_u64 v[234:235], s[58:59], 0, v[148:149]
	global_load_lds_dwordx4 v[232:233], off
	v_lshl_add_u64 v[232:233], s[78:79], 0, v[150:151]
	s_add_i32 m0, s77, 0x2000
	s_nop 0
	global_load_lds_dwordx4 v[232:233], off
	v_lshl_add_u64 v[232:233], s[58:59], 0, v[144:145]
	s_mov_b32 m0, s57
	s_nop 0
	global_load_lds_dwordx4 v[232:233], off
	s_mov_b32 m0, s65
	s_nop 0
	global_load_lds_dwordx4 v[234:235], off
	s_waitcnt vmcnt(8)
	s_waitcnt lgkmcnt(0)
	s_setprio 1
	s_barrier
	v_mfma_f32_16x16x32_bf16 v[76:79], v[48:51], v[204:207], v[76:79]
	v_mfma_f32_16x16x32_bf16 v[72:75], v[56:59], v[204:207], v[72:75]
	v_mfma_f32_16x16x32_bf16 v[76:79], v[52:55], v[208:211], v[76:79]
	v_mfma_f32_16x16x32_bf16 v[72:75], v[60:63], v[208:211], v[72:75]
	v_mfma_f32_16x16x32_bf16 v[44:47], v[48:51], v[212:215], v[44:47]
	v_mfma_f32_16x16x32_bf16 v[40:43], v[56:59], v[212:215], v[40:43]
	v_mfma_f32_16x16x32_bf16 v[44:47], v[52:55], v[216:219], v[44:47]
	v_mfma_f32_16x16x32_bf16 v[40:43], v[60:63], v[216:219], v[40:43]
	v_mfma_f32_16x16x32_bf16 v[28:31], v[48:51], v[220:223], v[28:31]
	v_mfma_f32_16x16x32_bf16 v[24:27], v[56:59], v[220:223], v[24:27]
	v_mfma_f32_16x16x32_bf16 v[28:31], v[52:55], v[224:227], v[28:31]
	v_mfma_f32_16x16x32_bf16 v[24:27], v[60:63], v[224:227], v[24:27]
	v_mfma_f32_16x16x32_bf16 v[12:15], v[48:51], v[240:243], v[12:15]
	v_mfma_f32_16x16x32_bf16 v[8:11], v[56:59], v[240:243], v[8:11]
	v_mfma_f32_16x16x32_bf16 v[12:15], v[52:55], v[244:247], v[12:15]
	v_mfma_f32_16x16x32_bf16 v[8:11], v[60:63], v[244:247], v[8:11]
	v_mfma_f32_16x16x32_bf16 v[36:39], v[164:167], v[212:215], v[36:39]
	v_mfma_f32_16x16x32_bf16 v[32:35], v[174:177], v[212:215], v[32:35]
	v_mfma_f32_16x16x32_bf16 v[36:39], v[170:173], v[216:219], v[36:39]
	v_mfma_f32_16x16x32_bf16 v[32:35], v[178:181], v[216:219], v[32:35]
	v_mfma_f32_16x16x32_bf16 v[20:23], v[164:167], v[220:223], v[20:23]
	v_mfma_f32_16x16x32_bf16 v[16:19], v[174:177], v[220:223], v[16:19]
	v_mfma_f32_16x16x32_bf16 v[20:23], v[170:173], v[224:227], v[20:23]
	v_mfma_f32_16x16x32_bf16 v[16:19], v[178:181], v[224:227], v[16:19]
	v_mfma_f32_16x16x32_bf16 v[4:7], v[164:167], v[240:243], v[4:7]
	v_mfma_f32_16x16x32_bf16 v[0:3], v[174:177], v[240:243], v[0:3]
	v_mfma_f32_16x16x32_bf16 v[4:7], v[170:173], v[244:247], v[4:7]
	v_mfma_f32_16x16x32_bf16 v[0:3], v[178:181], v[244:247], v[0:3]
	v_mfma_f32_16x16x32_bf16 v[48:51], v[164:167], v[204:207], v[68:71]
	v_mfma_f32_16x16x32_bf16 v[52:55], v[174:177], v[204:207], v[64:67]
	v_mfma_f32_16x16x32_bf16 v[48:51], v[170:173], v[208:211], v[48:51]
	v_mfma_f32_16x16x32_bf16 v[52:55], v[178:181], v[208:211], v[52:55]
	s_barrier
	s_setprio 0
	s_add_i32 s77, 0, 0x18000
	s_add_i32 s78, 0, 0x1c000
	v_add_u32_e32 v68, s77, v183
	v_add_u32_e32 v168, s78, v183
	ds_read_b128 v[56:59], v68
	ds_read_b128 v[60:63], v68 offset:1024
	ds_read_b128 v[64:67], v68 offset:2048
	ds_read_b128 v[68:71], v68 offset:3072
	ds_read_b128 v[164:167], v168
	ds_read_b128 v[170:173], v168 offset:1024
	ds_read_b128 v[174:177], v168 offset:2048
	ds_read_b128 v[178:181], v168 offset:3072
	s_add_u32 s58, s58, 0x40000
	s_addc_u32 s59, s59, 0
	s_mov_b32 m0, s66
	v_lshl_add_u64 v[236:237], s[58:59], 0, v[144:145]
	ds_read_b128 v[204:207], v202 offset:32768
	ds_read_b128 v[208:211], v202 offset:33792
	ds_read_b128 v[212:215], v202 offset:34816
	ds_read_b128 v[216:219], v202 offset:35840
	ds_read_b128 v[220:223], v202 offset:36864
	ds_read_b128 v[224:227], v202 offset:37888
	ds_read_b128 v[240:243], v202 offset:38912
	ds_read_b128 v[244:247], v202 offset:39936
	global_load_lds_dwordx4 v[236:237], off
	v_lshl_add_u64 v[236:237], s[58:59], 0, v[148:149]
	s_mov_b32 m0, s67
	s_nop 0
	global_load_lds_dwordx4 v[236:237], off
	s_waitcnt vmcnt(8)
	s_waitcnt lgkmcnt(0)
	s_setprio 1
	s_barrier
	v_mfma_f32_16x16x32_bf16 v[140:143], v[56:59], v[204:207], v[140:143]
	v_mfma_f32_16x16x32_bf16 v[136:139], v[64:67], v[204:207], v[136:139]
	v_mfma_f32_16x16x32_bf16 v[140:143], v[60:63], v[208:211], v[140:143]
	v_mfma_f32_16x16x32_bf16 v[136:139], v[68:71], v[208:211], v[136:139]
	v_mfma_f32_16x16x32_bf16 v[124:127], v[56:59], v[212:215], v[124:127]
	v_mfma_f32_16x16x32_bf16 v[120:123], v[64:67], v[212:215], v[120:123]
	v_mfma_f32_16x16x32_bf16 v[124:127], v[60:63], v[216:219], v[124:127]
	v_mfma_f32_16x16x32_bf16 v[120:123], v[68:71], v[216:219], v[120:123]
	v_mfma_f32_16x16x32_bf16 v[108:111], v[56:59], v[220:223], v[108:111]
	v_mfma_f32_16x16x32_bf16 v[104:107], v[64:67], v[220:223], v[104:107]
	v_mfma_f32_16x16x32_bf16 v[108:111], v[60:63], v[224:227], v[108:111]
	v_mfma_f32_16x16x32_bf16 v[104:107], v[68:71], v[224:227], v[104:107]
	v_mfma_f32_16x16x32_bf16 v[92:95], v[56:59], v[240:243], v[92:95]
	v_mfma_f32_16x16x32_bf16 v[88:91], v[64:67], v[240:243], v[88:91]
	v_mfma_f32_16x16x32_bf16 v[92:95], v[60:63], v[244:247], v[92:95]
	v_mfma_f32_16x16x32_bf16 v[88:91], v[68:71], v[244:247], v[88:91]
	v_mfma_f32_16x16x32_bf16 v[132:135], v[164:167], v[204:207], v[132:135]
	v_mfma_f32_16x16x32_bf16 v[128:131], v[174:177], v[204:207], v[128:131]
	v_mfma_f32_16x16x32_bf16 v[132:135], v[170:173], v[208:211], v[132:135]
	v_mfma_f32_16x16x32_bf16 v[128:131], v[178:181], v[208:211], v[128:131]
	v_mfma_f32_16x16x32_bf16 v[116:119], v[164:167], v[212:215], v[116:119]
	v_mfma_f32_16x16x32_bf16 v[112:115], v[174:177], v[212:215], v[112:115]
	v_mfma_f32_16x16x32_bf16 v[116:119], v[170:173], v[216:219], v[116:119]
	v_mfma_f32_16x16x32_bf16 v[112:115], v[178:181], v[216:219], v[112:115]
	v_mfma_f32_16x16x32_bf16 v[100:103], v[164:167], v[220:223], v[100:103]
	v_mfma_f32_16x16x32_bf16 v[96:99], v[174:177], v[220:223], v[96:99]
	v_mfma_f32_16x16x32_bf16 v[100:103], v[170:173], v[224:227], v[100:103]
	v_mfma_f32_16x16x32_bf16 v[96:99], v[178:181], v[224:227], v[96:99]
	v_mfma_f32_16x16x32_bf16 v[84:87], v[164:167], v[240:243], v[84:87]
	v_mfma_f32_16x16x32_bf16 v[80:83], v[174:177], v[240:243], v[80:83]
	v_mfma_f32_16x16x32_bf16 v[84:87], v[170:173], v[244:247], v[84:87]
	v_mfma_f32_16x16x32_bf16 v[80:83], v[178:181], v[244:247], v[80:83]
	s_barrier
	s_setprio 0
	s_add_i32 s58, s77, s62
	v_lshl_add_u64 v[228:229], v[228:229], 0, s[36:37]
	s_mov_b32 m0, s58
	ds_read_b128 v[204:207], v202 offset:49152
	ds_read_b128 v[208:211], v202 offset:50176
	ds_read_b128 v[212:215], v202 offset:51200
	ds_read_b128 v[216:219], v202 offset:52224
	ds_read_b128 v[220:223], v202 offset:53248
	ds_read_b128 v[224:227], v202 offset:54272
	ds_read_b128 v[240:243], v202 offset:55296
	ds_read_b128 v[244:247], v202 offset:56320
	global_load_lds_dwordx4 v[228:229], off
	s_add_i32 m0, s58, 0x2000
	s_add_u32 s20, s20, 0x40080
	v_lshl_add_u64 v[228:229], v[230:231], 0, s[36:37]
	s_addc_u32 s21, s21, 0
	s_add_i32 s58, s78, s62
	global_load_lds_dwordx4 v[228:229], off
	v_lshl_add_u64 v[228:229], s[20:21], 0, v[146:147]
	s_mov_b32 m0, s58
	s_nop 0
	global_load_lds_dwordx4 v[228:229], off
	v_lshl_add_u64 v[228:229], s[20:21], 0, v[150:151]
	s_add_i32 m0, s58, 0x2000
	s_nop 0
	global_load_lds_dwordx4 v[228:229], off
	v_lshl_add_u64 v[228:229], v[232:233], 0, s[36:37]
	s_mov_b32 m0, s69
	s_nop 0
	global_load_lds_dwordx4 v[228:229], off
	v_lshl_add_u64 v[228:229], v[234:235], 0, s[36:37]
	s_mov_b32 m0, s70
	s_nop 0
	global_load_lds_dwordx4 v[228:229], off
	s_waitcnt vmcnt(8)
	s_waitcnt lgkmcnt(0)
	s_setprio 1
	s_barrier
	v_mfma_f32_16x16x32_bf16 v[76:79], v[56:59], v[204:207], v[76:79]
	v_mfma_f32_16x16x32_bf16 v[72:75], v[64:67], v[204:207], v[72:75]
	v_mfma_f32_16x16x32_bf16 v[76:79], v[60:63], v[208:211], v[76:79]
	v_mfma_f32_16x16x32_bf16 v[72:75], v[68:71], v[208:211], v[72:75]
	v_mfma_f32_16x16x32_bf16 v[44:47], v[56:59], v[212:215], v[44:47]
	v_mfma_f32_16x16x32_bf16 v[40:43], v[64:67], v[212:215], v[40:43]
	v_mfma_f32_16x16x32_bf16 v[44:47], v[60:63], v[216:219], v[44:47]
	v_mfma_f32_16x16x32_bf16 v[40:43], v[68:71], v[216:219], v[40:43]
	v_mfma_f32_16x16x32_bf16 v[28:31], v[56:59], v[220:223], v[28:31]
	v_mfma_f32_16x16x32_bf16 v[24:27], v[64:67], v[220:223], v[24:27]
	v_mfma_f32_16x16x32_bf16 v[28:31], v[60:63], v[224:227], v[28:31]
	v_mfma_f32_16x16x32_bf16 v[24:27], v[68:71], v[224:227], v[24:27]
	v_mfma_f32_16x16x32_bf16 v[12:15], v[56:59], v[240:243], v[12:15]
	v_mfma_f32_16x16x32_bf16 v[8:11], v[64:67], v[240:243], v[8:11]
	v_mfma_f32_16x16x32_bf16 v[12:15], v[60:63], v[244:247], v[12:15]
	v_mfma_f32_16x16x32_bf16 v[8:11], v[68:71], v[244:247], v[8:11]
	v_mfma_f32_16x16x32_bf16 v[48:51], v[164:167], v[204:207], v[48:51]
	v_mfma_f32_16x16x32_bf16 v[68:71], v[170:173], v[208:211], v[48:51]
	v_mfma_f32_16x16x32_bf16 v[48:51], v[174:177], v[204:207], v[52:55]
	v_mfma_f32_16x16x32_bf16 v[36:39], v[164:167], v[212:215], v[36:39]
	v_mfma_f32_16x16x32_bf16 v[32:35], v[174:177], v[212:215], v[32:35]
	v_mfma_f32_16x16x32_bf16 v[20:23], v[164:167], v[220:223], v[20:23]
	v_mfma_f32_16x16x32_bf16 v[16:19], v[174:177], v[220:223], v[16:19]
	v_mfma_f32_16x16x32_bf16 v[4:7], v[164:167], v[240:243], v[4:7]
	v_mfma_f32_16x16x32_bf16 v[0:3], v[174:177], v[240:243], v[0:3]
	v_mfma_f32_16x16x32_bf16 v[64:67], v[178:181], v[208:211], v[48:51]
	v_mfma_f32_16x16x32_bf16 v[36:39], v[170:173], v[216:219], v[36:39]
	v_mfma_f32_16x16x32_bf16 v[32:35], v[178:181], v[216:219], v[32:35]
	v_mfma_f32_16x16x32_bf16 v[20:23], v[170:173], v[224:227], v[20:23]
	v_mfma_f32_16x16x32_bf16 v[16:19], v[178:181], v[224:227], v[16:19]
	v_mfma_f32_16x16x32_bf16 v[4:7], v[170:173], v[244:247], v[4:7]
	v_mfma_f32_16x16x32_bf16 v[0:3], v[178:181], v[244:247], v[0:3]
	s_barrier
	s_setprio 0
	s_add_i32 s76, s76, 2
	s_add_u32 s74, s74, 0x100
	s_addc_u32 s75, s75, 0
	s_add_u32 s40, s40, 0x100
	s_addc_u32 s41, s41, 0
	s_cmp_gt_u32 s76, 13
	s_cbranch_scc0 .LBB0_320
	s_and_b64 vcc, exec, s[42:43]
	s_cbranch_vccz .LBB0_323
	s_barrier

.LBB0_478:
	s_add_u32 s20, s40, 0xfffc0080
	s_addc_u32 s21, s41, -1
	s_add_i32 s65, 0, 0x10000
	s_cmp_eq_u32 s64, 12
	s_cselect_b32 s43, s15, s21
	s_cselect_b32 s42, s45, s20
	v_add_u32_e32 v167, s65, v149
	s_cselect_b32 s21, s13, s63
	s_cselect_b32 s20, s61, s62
	s_add_i32 s68, 0, 0x14000
	ds_read_b128 v[140:143], v167
	ds_read_b128 v[144:147], v167 offset:1024
	ds_read_b128 v[170:173], v167 offset:2048
	ds_read_b128 v[174:177], v167 offset:3072
	v_add_u32_e32 v167, s68, v149
	ds_read_b128 v[178:181], v167
	ds_read_b128 v[182:185], v167 offset:1024
	ds_read_b128 v[186:189], v167 offset:2048
	ds_read_b128 v[190:193], v167 offset:3072
	v_lshl_add_u64 v[226:227], s[40:41], 0, v[138:139]
	s_add_i32 m0, s53, 0xc000
	ds_read_b128 v[194:197], v166
	ds_read_b128 v[198:201], v166 offset:1024
	ds_read_b128 v[202:205], v166 offset:2048
	ds_read_b128 v[206:209], v166 offset:3072
	ds_read_b128 v[210:213], v166 offset:4096
	ds_read_b128 v[214:217], v166 offset:5120
	ds_read_b128 v[218:221], v166 offset:6144
	ds_read_b128 v[222:225], v166 offset:7168
	global_load_lds_dwordx4 v[226:227], off
	v_lshl_add_u64 v[226:227], s[40:41], 0, v[136:137]
	s_add_i32 m0, s53, 0xe000
	s_nop 0
	global_load_lds_dwordx4 v[226:227], off
	s_waitcnt vmcnt(8)
	s_waitcnt lgkmcnt(0)
	s_setprio 1
	s_barrier
	v_mfma_f32_16x16x32_bf16 v[124:127], v[140:143], v[194:197], v[124:127]
	v_mfma_f32_16x16x32_bf16 v[120:123], v[170:173], v[194:197], v[120:123]
	v_mfma_f32_16x16x32_bf16 v[124:127], v[144:147], v[198:201], v[124:127]
	v_mfma_f32_16x16x32_bf16 v[120:123], v[174:177], v[198:201], v[120:123]
	v_mfma_f32_16x16x32_bf16 v[108:111], v[140:143], v[202:205], v[108:111]
	v_mfma_f32_16x16x32_bf16 v[104:107], v[170:173], v[202:205], v[104:107]
	v_mfma_f32_16x16x32_bf16 v[108:111], v[144:147], v[206:209], v[108:111]
	v_mfma_f32_16x16x32_bf16 v[104:107], v[174:177], v[206:209], v[104:107]
	v_mfma_f32_16x16x32_bf16 v[92:95], v[140:143], v[210:213], v[92:95]
	v_mfma_f32_16x16x32_bf16 v[88:91], v[170:173], v[210:213], v[88:91]
	v_mfma_f32_16x16x32_bf16 v[92:95], v[144:147], v[214:217], v[92:95]
	v_mfma_f32_16x16x32_bf16 v[88:91], v[174:177], v[214:217], v[88:91]
	v_mfma_f32_16x16x32_bf16 v[76:79], v[140:143], v[218:221], v[76:79]
	v_mfma_f32_16x16x32_bf16 v[72:75], v[170:173], v[218:221], v[72:75]
	v_mfma_f32_16x16x32_bf16 v[76:79], v[144:147], v[222:225], v[76:79]
	v_mfma_f32_16x16x32_bf16 v[72:75], v[174:177], v[222:225], v[72:75]
	v_mfma_f32_16x16x32_bf16 v[116:119], v[178:181], v[194:197], v[116:119]
	v_mfma_f32_16x16x32_bf16 v[112:115], v[186:189], v[194:197], v[112:115]
	v_mfma_f32_16x16x32_bf16 v[116:119], v[182:185], v[198:201], v[116:119]
	v_mfma_f32_16x16x32_bf16 v[112:115], v[190:193], v[198:201], v[112:115]
	v_mfma_f32_16x16x32_bf16 v[100:103], v[178:181], v[202:205], v[100:103]
	v_mfma_f32_16x16x32_bf16 v[96:99], v[186:189], v[202:205], v[96:99]
	v_mfma_f32_16x16x32_bf16 v[100:103], v[182:185], v[206:209], v[100:103]
	v_mfma_f32_16x16x32_bf16 v[96:99], v[190:193], v[206:209], v[96:99]
	v_mfma_f32_16x16x32_bf16 v[84:87], v[178:181], v[210:213], v[84:87]
	v_mfma_f32_16x16x32_bf16 v[80:83], v[186:189], v[210:213], v[80:83]
	v_mfma_f32_16x16x32_bf16 v[84:87], v[182:185], v[214:217], v[84:87]
	v_mfma_f32_16x16x32_bf16 v[80:83], v[190:193], v[214:217], v[80:83]
	v_mfma_f32_16x16x32_bf16 v[68:71], v[178:181], v[218:221], v[68:71]
	v_mfma_f32_16x16x32_bf16 v[64:67], v[186:189], v[218:221], v[64:67]
	v_mfma_f32_16x16x32_bf16 v[68:71], v[182:185], v[222:225], v[68:71]
	v_mfma_f32_16x16x32_bf16 v[64:67], v[190:193], v[222:225], v[64:67]
	s_barrier
	s_setprio 0
	s_add_i32 s65, s65, s50
	v_lshl_add_u64 v[226:227], s[20:21], 0, v[132:133]
	s_mov_b32 m0, s65
	ds_read_b128 v[194:197], v166 offset:16384
	ds_read_b128 v[198:201], v166 offset:17408
	ds_read_b128 v[202:205], v166 offset:18432
	ds_read_b128 v[206:209], v166 offset:19456
	ds_read_b128 v[210:213], v166 offset:20480
	ds_read_b128 v[214:217], v166 offset:21504
	ds_read_b128 v[218:221], v166 offset:22528
	ds_read_b128 v[222:225], v166 offset:23552
	global_load_lds_dwordx4 v[226:227], off
	s_add_i32 m0, s65, 0x2000
	s_add_u32 s66, s20, 0x40000
	v_lshl_add_u64 v[228:229], s[20:21], 0, v[128:129]
	s_addc_u32 s67, s21, 0
	s_add_i32 s65, s68, s50
	global_load_lds_dwordx4 v[228:229], off
	v_lshl_add_u64 v[230:231], s[66:67], 0, v[132:133]
	s_mov_b32 m0, s65
	v_lshl_add_u64 v[232:233], s[42:43], 0, v[130:131]
	global_load_lds_dwordx4 v[230:231], off
	v_lshl_add_u64 v[230:231], s[66:67], 0, v[128:129]
	s_add_i32 m0, s65, 0x2000
	s_nop 0
	global_load_lds_dwordx4 v[230:231], off
	v_lshl_add_u64 v[230:231], s[42:43], 0, v[134:135]
	s_mov_b32 m0, s53
	s_nop 0
	global_load_lds_dwordx4 v[230:231], off
	s_mov_b32 m0, s54
	s_nop 0
	global_load_lds_dwordx4 v[232:233], off
	s_waitcnt vmcnt(8)
	s_waitcnt lgkmcnt(0)
	s_setprio 1
	s_barrier
	v_mfma_f32_16x16x32_bf16 v[60:63], v[140:143], v[194:197], v[60:63]
	v_mfma_f32_16x16x32_bf16 v[56:59], v[170:173], v[194:197], v[56:59]
	v_mfma_f32_16x16x32_bf16 v[60:63], v[144:147], v[198:201], v[60:63]
	v_mfma_f32_16x16x32_bf16 v[56:59], v[174:177], v[198:201], v[56:59]
	v_mfma_f32_16x16x32_bf16 v[44:47], v[140:143], v[202:205], v[44:47]
	v_mfma_f32_16x16x32_bf16 v[40:43], v[170:173], v[202:205], v[40:43]
	v_mfma_f32_16x16x32_bf16 v[44:47], v[144:147], v[206:209], v[44:47]
	v_mfma_f32_16x16x32_bf16 v[40:43], v[174:177], v[206:209], v[40:43]
	v_mfma_f32_16x16x32_bf16 v[28:31], v[140:143], v[210:213], v[28:31]
	v_mfma_f32_16x16x32_bf16 v[24:27], v[170:173], v[210:213], v[24:27]
	v_mfma_f32_16x16x32_bf16 v[28:31], v[144:147], v[214:217], v[28:31]
	v_mfma_f32_16x16x32_bf16 v[24:27], v[174:177], v[214:217], v[24:27]
	v_mfma_f32_16x16x32_bf16 v[12:15], v[140:143], v[218:221], v[12:15]
	v_mfma_f32_16x16x32_bf16 v[8:11], v[170:173], v[218:221], v[8:11]
	v_mfma_f32_16x16x32_bf16 v[12:15], v[144:147], v[222:225], v[12:15]
	v_mfma_f32_16x16x32_bf16 v[8:11], v[174:177], v[222:225], v[8:11]
	v_mfma_f32_16x16x32_bf16 v[52:55], v[178:181], v[194:197], v[52:55]
	v_mfma_f32_16x16x32_bf16 v[48:51], v[186:189], v[194:197], v[48:51]
	v_mfma_f32_16x16x32_bf16 v[52:55], v[182:185], v[198:201], v[52:55]
	v_mfma_f32_16x16x32_bf16 v[48:51], v[190:193], v[198:201], v[48:51]
	v_mfma_f32_16x16x32_bf16 v[36:39], v[178:181], v[202:205], v[36:39]
	v_mfma_f32_16x16x32_bf16 v[32:35], v[186:189], v[202:205], v[32:35]
	v_mfma_f32_16x16x32_bf16 v[36:39], v[182:185], v[206:209], v[36:39]
	v_mfma_f32_16x16x32_bf16 v[32:35], v[190:193], v[206:209], v[32:35]
	v_mfma_f32_16x16x32_bf16 v[20:23], v[178:181], v[210:213], v[20:23]
	v_mfma_f32_16x16x32_bf16 v[16:19], v[186:189], v[210:213], v[16:19]
	v_mfma_f32_16x16x32_bf16 v[20:23], v[182:185], v[214:217], v[20:23]
	v_mfma_f32_16x16x32_bf16 v[16:19], v[190:193], v[214:217], v[16:19]
	v_mfma_f32_16x16x32_bf16 v[4:7], v[178:181], v[218:221], v[4:7]
	v_mfma_f32_16x16x32_bf16 v[0:3], v[186:189], v[218:221], v[0:3]
	v_mfma_f32_16x16x32_bf16 v[4:7], v[182:185], v[222:225], v[4:7]
	v_mfma_f32_16x16x32_bf16 v[0:3], v[190:193], v[222:225], v[0:3]
	s_barrier
	s_setprio 0
	s_add_i32 s65, 0, 0x18000
	v_add_u32_e32 v167, s65, v149
	s_add_i32 s66, 0, 0x1c000
	ds_read_b128 v[140:143], v167
	ds_read_b128 v[144:147], v167 offset:1024
	ds_read_b128 v[170:173], v167 offset:2048
	ds_read_b128 v[174:177], v167 offset:3072
	v_add_u32_e32 v167, s66, v149
	ds_read_b128 v[178:181], v167
	ds_read_b128 v[182:185], v167 offset:1024
	ds_read_b128 v[186:189], v167 offset:2048
	ds_read_b128 v[190:193], v167 offset:3072
	s_add_u32 s42, s42, 0x40000
	s_addc_u32 s43, s43, 0
	s_mov_b32 m0, s55
	v_lshl_add_u64 v[234:235], s[42:43], 0, v[134:135]
	ds_read_b128 v[194:197], v166 offset:32768
	ds_read_b128 v[198:201], v166 offset:33792
	ds_read_b128 v[202:205], v166 offset:34816
	ds_read_b128 v[206:209], v166 offset:35840
	ds_read_b128 v[210:213], v166 offset:36864
	ds_read_b128 v[214:217], v166 offset:37888
	ds_read_b128 v[218:221], v166 offset:38912
	ds_read_b128 v[222:225], v166 offset:39936
	global_load_lds_dwordx4 v[234:235], off
	v_lshl_add_u64 v[234:235], s[42:43], 0, v[130:131]
	s_mov_b32 m0, s56
	s_nop 0
	global_load_lds_dwordx4 v[234:235], off
	s_waitcnt vmcnt(8)
	s_waitcnt lgkmcnt(0)
	s_setprio 1
	s_barrier
	v_mfma_f32_16x16x32_bf16 v[124:127], v[140:143], v[194:197], v[124:127]
	v_mfma_f32_16x16x32_bf16 v[120:123], v[170:173], v[194:197], v[120:123]
	v_mfma_f32_16x16x32_bf16 v[124:127], v[144:147], v[198:201], v[124:127]
	v_mfma_f32_16x16x32_bf16 v[120:123], v[174:177], v[198:201], v[120:123]
	v_mfma_f32_16x16x32_bf16 v[108:111], v[140:143], v[202:205], v[108:111]
	v_mfma_f32_16x16x32_bf16 v[104:107], v[170:173], v[202:205], v[104:107]
	v_mfma_f32_16x16x32_bf16 v[108:111], v[144:147], v[206:209], v[108:111]
	v_mfma_f32_16x16x32_bf16 v[104:107], v[174:177], v[206:209], v[104:107]
	v_mfma_f32_16x16x32_bf16 v[92:95], v[140:143], v[210:213], v[92:95]
	v_mfma_f32_16x16x32_bf16 v[88:91], v[170:173], v[210:213], v[88:91]
	v_mfma_f32_16x16x32_bf16 v[92:95], v[144:147], v[214:217], v[92:95]
	v_mfma_f32_16x16x32_bf16 v[88:91], v[174:177], v[214:217], v[88:91]
	v_mfma_f32_16x16x32_bf16 v[76:79], v[140:143], v[218:221], v[76:79]
	v_mfma_f32_16x16x32_bf16 v[72:75], v[170:173], v[218:221], v[72:75]
	v_mfma_f32_16x16x32_bf16 v[76:79], v[144:147], v[222:225], v[76:79]
	v_mfma_f32_16x16x32_bf16 v[72:75], v[174:177], v[222:225], v[72:75]
	v_mfma_f32_16x16x32_bf16 v[116:119], v[178:181], v[194:197], v[116:119]
	v_mfma_f32_16x16x32_bf16 v[112:115], v[186:189], v[194:197], v[112:115]
	v_mfma_f32_16x16x32_bf16 v[116:119], v[182:185], v[198:201], v[116:119]
	v_mfma_f32_16x16x32_bf16 v[112:115], v[190:193], v[198:201], v[112:115]
	v_mfma_f32_16x16x32_bf16 v[100:103], v[178:181], v[202:205], v[100:103]
	v_mfma_f32_16x16x32_bf16 v[96:99], v[186:189], v[202:205], v[96:99]
	v_mfma_f32_16x16x32_bf16 v[100:103], v[182:185], v[206:209], v[100:103]
	v_mfma_f32_16x16x32_bf16 v[96:99], v[190:193], v[206:209], v[96:99]
	v_mfma_f32_16x16x32_bf16 v[84:87], v[178:181], v[210:213], v[84:87]
	v_mfma_f32_16x16x32_bf16 v[80:83], v[186:189], v[210:213], v[80:83]
	v_mfma_f32_16x16x32_bf16 v[84:87], v[182:185], v[214:217], v[84:87]
	v_mfma_f32_16x16x32_bf16 v[80:83], v[190:193], v[214:217], v[80:83]
	v_mfma_f32_16x16x32_bf16 v[68:71], v[178:181], v[218:221], v[68:71]
	v_mfma_f32_16x16x32_bf16 v[64:67], v[186:189], v[218:221], v[64:67]
	v_mfma_f32_16x16x32_bf16 v[68:71], v[182:185], v[222:225], v[68:71]
	v_mfma_f32_16x16x32_bf16 v[64:67], v[190:193], v[222:225], v[64:67]
	s_barrier
	s_setprio 0
	s_add_i32 s42, s65, s50
	v_lshl_add_u64 v[226:227], v[226:227], 0, s[36:37]
	s_mov_b32 m0, s42
	ds_read_b128 v[194:197], v166 offset:49152
	ds_read_b128 v[198:201], v166 offset:50176
	ds_read_b128 v[202:205], v166 offset:51200
	ds_read_b128 v[206:209], v166 offset:52224
	ds_read_b128 v[210:213], v166 offset:53248
	ds_read_b128 v[214:217], v166 offset:54272
	ds_read_b128 v[218:221], v166 offset:55296
	ds_read_b128 v[222:225], v166 offset:56320
	global_load_lds_dwordx4 v[226:227], off
	s_add_i32 m0, s42, 0x2000
	s_add_u32 s20, s20, 0x40080
	v_lshl_add_u64 v[226:227], v[228:229], 0, s[36:37]
	s_addc_u32 s21, s21, 0
	s_add_i32 s42, s66, s50
	global_load_lds_dwordx4 v[226:227], off
	v_lshl_add_u64 v[226:227], s[20:21], 0, v[132:133]
	s_mov_b32 m0, s42
	s_nop 0
	global_load_lds_dwordx4 v[226:227], off
	v_lshl_add_u64 v[226:227], s[20:21], 0, v[128:129]
	s_add_i32 m0, s42, 0x2000
	s_nop 0
	global_load_lds_dwordx4 v[226:227], off
	v_lshl_add_u64 v[226:227], v[230:231], 0, s[36:37]
	s_mov_b32 m0, s57
	s_nop 0
	global_load_lds_dwordx4 v[226:227], off
	v_lshl_add_u64 v[226:227], v[232:233], 0, s[36:37]
	s_mov_b32 m0, s58
	s_nop 0
	global_load_lds_dwordx4 v[226:227], off
	s_waitcnt vmcnt(8)
	s_waitcnt lgkmcnt(0)
	s_setprio 1
	s_barrier
	v_mfma_f32_16x16x32_bf16 v[60:63], v[140:143], v[194:197], v[60:63]
	v_mfma_f32_16x16x32_bf16 v[56:59], v[170:173], v[194:197], v[56:59]
	v_mfma_f32_16x16x32_bf16 v[60:63], v[144:147], v[198:201], v[60:63]
	v_mfma_f32_16x16x32_bf16 v[56:59], v[174:177], v[198:201], v[56:59]
	v_mfma_f32_16x16x32_bf16 v[44:47], v[140:143], v[202:205], v[44:47]
	v_mfma_f32_16x16x32_bf16 v[40:43], v[170:173], v[202:205], v[40:43]
	v_mfma_f32_16x16x32_bf16 v[44:47], v[144:147], v[206:209], v[44:47]
	v_mfma_f32_16x16x32_bf16 v[40:43], v[174:177], v[206:209], v[40:43]
	v_mfma_f32_16x16x32_bf16 v[28:31], v[140:143], v[210:213], v[28:31]
	v_mfma_f32_16x16x32_bf16 v[24:27], v[170:173], v[210:213], v[24:27]
	v_mfma_f32_16x16x32_bf16 v[28:31], v[144:147], v[214:217], v[28:31]
	v_mfma_f32_16x16x32_bf16 v[24:27], v[174:177], v[214:217], v[24:27]
	v_mfma_f32_16x16x32_bf16 v[12:15], v[140:143], v[218:221], v[12:15]
	v_mfma_f32_16x16x32_bf16 v[8:11], v[170:173], v[218:221], v[8:11]
	v_mfma_f32_16x16x32_bf16 v[12:15], v[144:147], v[222:225], v[12:15]
	v_mfma_f32_16x16x32_bf16 v[8:11], v[174:177], v[222:225], v[8:11]
	v_mfma_f32_16x16x32_bf16 v[52:55], v[178:181], v[194:197], v[52:55]
	v_mfma_f32_16x16x32_bf16 v[48:51], v[186:189], v[194:197], v[48:51]
	v_mfma_f32_16x16x32_bf16 v[52:55], v[182:185], v[198:201], v[52:55]
	v_mfma_f32_16x16x32_bf16 v[48:51], v[190:193], v[198:201], v[48:51]
	v_mfma_f32_16x16x32_bf16 v[36:39], v[178:181], v[202:205], v[36:39]
	v_mfma_f32_16x16x32_bf16 v[32:35], v[186:189], v[202:205], v[32:35]
	v_mfma_f32_16x16x32_bf16 v[36:39], v[182:185], v[206:209], v[36:39]
	v_mfma_f32_16x16x32_bf16 v[32:35], v[190:193], v[206:209], v[32:35]
	v_mfma_f32_16x16x32_bf16 v[20:23], v[178:181], v[210:213], v[20:23]
	v_mfma_f32_16x16x32_bf16 v[16:19], v[186:189], v[210:213], v[16:19]
	v_mfma_f32_16x16x32_bf16 v[20:23], v[182:185], v[214:217], v[20:23]
	v_mfma_f32_16x16x32_bf16 v[16:19], v[190:193], v[214:217], v[16:19]
	v_mfma_f32_16x16x32_bf16 v[4:7], v[178:181], v[218:221], v[4:7]
	v_mfma_f32_16x16x32_bf16 v[0:3], v[186:189], v[218:221], v[0:3]
	v_mfma_f32_16x16x32_bf16 v[4:7], v[182:185], v[222:225], v[4:7]
	v_mfma_f32_16x16x32_bf16 v[0:3], v[190:193], v[222:225], v[0:3]
	s_barrier
	s_setprio 0
	s_add_i32 s64, s64, 2
	s_add_u32 s62, s62, 0x100
	s_addc_u32 s63, s63, 0
	s_add_u32 s40, s40, 0x100
	s_addc_u32 s41, s41, 0
	s_cmp_gt_u32 s64, 13
	s_cbranch_scc0 .LBB0_478
	s_and_b64 vcc, exec, s[8:9]
	s_cbranch_vccz .LBB0_481
	s_barrier

.LBB0_575:
	s_add_i32 s54, s20, 2
	s_add_u32 s55, s42, 0x80
	s_addc_u32 s21, s43, 0
	s_add_i32 s74, 0, 0x10000
	s_cmp_eq_u32 s31, s20
	s_cselect_b32 s21, s51, s21
	s_cselect_b32 s20, s50, s55
	s_cselect_b32 s73, s53, s45
	s_cselect_b32 s72, s52, s44
	s_add_i32 s55, 0, 0x14000
	v_add_u32_e32 v124, s74, v207
	v_add_u32_e32 v166, s55, v207
	ds_read_b128 v[88:91], v124
	ds_read_b128 v[100:103], v124 offset:1024
	ds_read_b128 v[112:115], v124 offset:2048
	ds_read_b128 v[124:127], v124 offset:3072
	ds_read_b128 v[136:139], v166
	ds_read_b128 v[148:151], v166 offset:1024
	ds_read_b128 v[152:155], v166 offset:2048
	ds_read_b128 v[170:173], v166 offset:3072
	v_lshl_add_u64 v[166:167], s[42:43], 0, v[164:165]
	s_add_i32 m0, s61, 0xc000
	ds_read_b128 v[174:177], v211
	ds_read_b128 v[178:181], v211 offset:1024
	ds_read_b128 v[182:185], v211 offset:2048
	ds_read_b128 v[186:189], v211 offset:3072
	ds_read_b128 v[190:193], v211 offset:4096
	ds_read_b128 v[194:197], v211 offset:5120
	ds_read_b128 v[198:201], v211 offset:6144
	ds_read_b128 v[202:205], v211 offset:7168
	global_load_lds_dwordx4 v[166:167], off
	v_lshl_add_u64 v[166:167], s[42:43], 0, v[162:163]
	s_add_i32 m0, s61, 0xe000
	s_nop 0
	global_load_lds_dwordx4 v[166:167], off
	s_waitcnt vmcnt(8)
	s_waitcnt lgkmcnt(0)
	s_setprio 1
	s_barrier
	v_mfma_f32_16x16x32_bf16 v[144:147], v[88:91], v[174:177], v[144:147]
	v_mfma_f32_16x16x32_bf16 v[140:143], v[112:115], v[174:177], v[140:143]
	v_mfma_f32_16x16x32_bf16 v[144:147], v[100:103], v[178:181], v[144:147]
	v_mfma_f32_16x16x32_bf16 v[140:143], v[124:127], v[178:181], v[140:143]
	v_mfma_f32_16x16x32_bf16 v[120:123], v[88:91], v[182:185], v[120:123]
	v_mfma_f32_16x16x32_bf16 v[116:119], v[112:115], v[182:185], v[116:119]
	v_mfma_f32_16x16x32_bf16 v[120:123], v[100:103], v[186:189], v[120:123]
	v_mfma_f32_16x16x32_bf16 v[116:119], v[124:127], v[186:189], v[116:119]
	v_mfma_f32_16x16x32_bf16 v[96:99], v[88:91], v[190:193], v[96:99]
	v_mfma_f32_16x16x32_bf16 v[92:95], v[112:115], v[190:193], v[92:95]
	v_mfma_f32_16x16x32_bf16 v[96:99], v[100:103], v[194:197], v[96:99]
	v_mfma_f32_16x16x32_bf16 v[92:95], v[124:127], v[194:197], v[92:95]
	v_mfma_f32_16x16x32_bf16 v[76:79], v[88:91], v[198:201], v[76:79]
	v_mfma_f32_16x16x32_bf16 v[72:75], v[112:115], v[198:201], v[72:75]
	v_mfma_f32_16x16x32_bf16 v[76:79], v[100:103], v[202:205], v[76:79]
	v_mfma_f32_16x16x32_bf16 v[72:75], v[124:127], v[202:205], v[72:75]
	v_mfma_f32_16x16x32_bf16 v[132:135], v[136:139], v[174:177], v[132:135]
	v_mfma_f32_16x16x32_bf16 v[128:131], v[152:155], v[174:177], v[128:131]
	v_mfma_f32_16x16x32_bf16 v[132:135], v[148:151], v[178:181], v[132:135]
	v_mfma_f32_16x16x32_bf16 v[128:131], v[170:173], v[178:181], v[128:131]
	v_mfma_f32_16x16x32_bf16 v[108:111], v[136:139], v[182:185], v[108:111]
	v_mfma_f32_16x16x32_bf16 v[104:107], v[152:155], v[182:185], v[104:107]
	v_mfma_f32_16x16x32_bf16 v[108:111], v[148:151], v[186:189], v[108:111]
	v_mfma_f32_16x16x32_bf16 v[104:107], v[170:173], v[186:189], v[104:107]
	v_mfma_f32_16x16x32_bf16 v[84:87], v[136:139], v[190:193], v[84:87]
	v_mfma_f32_16x16x32_bf16 v[80:83], v[152:155], v[190:193], v[80:83]
	v_mfma_f32_16x16x32_bf16 v[84:87], v[148:151], v[194:197], v[84:87]
	v_mfma_f32_16x16x32_bf16 v[80:83], v[170:173], v[194:197], v[80:83]
	v_mfma_f32_16x16x32_bf16 v[68:71], v[136:139], v[198:201], v[68:71]
	v_mfma_f32_16x16x32_bf16 v[64:67], v[152:155], v[198:201], v[64:67]
	v_mfma_f32_16x16x32_bf16 v[68:71], v[148:151], v[202:205], v[68:71]
	v_mfma_f32_16x16x32_bf16 v[64:67], v[170:173], v[202:205], v[64:67]
	s_barrier
	s_setprio 0
	s_add_i32 s74, s74, s56
	v_lshl_add_u64 v[166:167], s[72:73], 0, v[168:169]
	s_mov_b32 m0, s74
	ds_read_b128 v[174:177], v211 offset:16384
	ds_read_b128 v[178:181], v211 offset:17408
	ds_read_b128 v[182:185], v211 offset:18432
	ds_read_b128 v[186:189], v211 offset:19456
	ds_read_b128 v[190:193], v211 offset:20480
	ds_read_b128 v[194:197], v211 offset:21504
	ds_read_b128 v[198:201], v211 offset:22528
	ds_read_b128 v[202:205], v211 offset:23552
	global_load_lds_dwordx4 v[166:167], off
	s_add_i32 m0, s74, 0x2000
	v_lshl_add_u64 v[212:213], s[72:73], 0, v[156:157]
	s_add_u32 s72, s72, s0
	s_addc_u32 s73, s73, 0
	s_add_i32 s55, s55, s56
	global_load_lds_dwordx4 v[212:213], off
	v_lshl_add_u64 v[214:215], s[72:73], 0, v[168:169]
	s_mov_b32 m0, s55
	v_lshl_add_u64 v[216:217], s[72:73], 0, v[156:157]
	global_load_lds_dwordx4 v[214:215], off
	s_add_i32 m0, s55, 0x2000
	v_lshl_add_u64 v[218:219], s[20:21], 0, v[160:161]
	global_load_lds_dwordx4 v[216:217], off
	s_mov_b32 m0, s61
	v_lshl_add_u64 v[220:221], s[20:21], 0, v[158:159]
	global_load_lds_dwordx4 v[218:219], off
	s_mov_b32 m0, s62
	s_nop 0
	global_load_lds_dwordx4 v[220:221], off
	s_waitcnt vmcnt(8)
	s_waitcnt lgkmcnt(0)
	s_setprio 1
	s_barrier
	v_mfma_f32_16x16x32_bf16 v[60:63], v[88:91], v[174:177], v[60:63]
	v_mfma_f32_16x16x32_bf16 v[56:59], v[112:115], v[174:177], v[56:59]
	v_mfma_f32_16x16x32_bf16 v[60:63], v[100:103], v[178:181], v[60:63]
	v_mfma_f32_16x16x32_bf16 v[56:59], v[124:127], v[178:181], v[56:59]
	v_mfma_f32_16x16x32_bf16 v[44:47], v[88:91], v[182:185], v[44:47]
	v_mfma_f32_16x16x32_bf16 v[40:43], v[112:115], v[182:185], v[40:43]
	v_mfma_f32_16x16x32_bf16 v[44:47], v[100:103], v[186:189], v[44:47]
	v_mfma_f32_16x16x32_bf16 v[40:43], v[124:127], v[186:189], v[40:43]
	v_mfma_f32_16x16x32_bf16 v[28:31], v[88:91], v[190:193], v[28:31]
	v_mfma_f32_16x16x32_bf16 v[24:27], v[112:115], v[190:193], v[24:27]
	v_mfma_f32_16x16x32_bf16 v[28:31], v[100:103], v[194:197], v[28:31]
	v_mfma_f32_16x16x32_bf16 v[24:27], v[124:127], v[194:197], v[24:27]
	v_mfma_f32_16x16x32_bf16 v[12:15], v[88:91], v[198:201], v[12:15]
	v_mfma_f32_16x16x32_bf16 v[8:11], v[112:115], v[198:201], v[8:11]
	v_mfma_f32_16x16x32_bf16 v[12:15], v[100:103], v[202:205], v[12:15]
	v_mfma_f32_16x16x32_bf16 v[8:11], v[124:127], v[202:205], v[8:11]
	v_mfma_f32_16x16x32_bf16 v[52:55], v[136:139], v[174:177], v[52:55]
	v_mfma_f32_16x16x32_bf16 v[48:51], v[152:155], v[174:177], v[48:51]
	v_mfma_f32_16x16x32_bf16 v[52:55], v[148:151], v[178:181], v[52:55]
	v_mfma_f32_16x16x32_bf16 v[48:51], v[170:173], v[178:181], v[48:51]
	v_mfma_f32_16x16x32_bf16 v[36:39], v[136:139], v[182:185], v[36:39]
	v_mfma_f32_16x16x32_bf16 v[32:35], v[152:155], v[182:185], v[32:35]
	v_mfma_f32_16x16x32_bf16 v[36:39], v[148:151], v[186:189], v[36:39]
	v_mfma_f32_16x16x32_bf16 v[32:35], v[170:173], v[186:189], v[32:35]
	v_mfma_f32_16x16x32_bf16 v[20:23], v[136:139], v[190:193], v[20:23]
	v_mfma_f32_16x16x32_bf16 v[16:19], v[152:155], v[190:193], v[16:19]
	v_mfma_f32_16x16x32_bf16 v[20:23], v[148:151], v[194:197], v[20:23]
	v_mfma_f32_16x16x32_bf16 v[16:19], v[170:173], v[194:197], v[16:19]
	v_mfma_f32_16x16x32_bf16 v[4:7], v[136:139], v[198:201], v[4:7]
	v_mfma_f32_16x16x32_bf16 v[0:3], v[152:155], v[198:201], v[0:3]
	v_mfma_f32_16x16x32_bf16 v[4:7], v[148:151], v[202:205], v[4:7]
	v_mfma_f32_16x16x32_bf16 v[0:3], v[170:173], v[202:205], v[0:3]
	s_barrier
	s_setprio 0
	s_add_i32 s55, 0, 0x18000
	s_add_i32 s72, 0, 0x1c000
	v_add_u32_e32 v124, s55, v207
	v_add_u32_e32 v170, s72, v207
	ds_read_b128 v[88:91], v124
	ds_read_b128 v[100:103], v124 offset:1024
	ds_read_b128 v[112:115], v124 offset:2048
	ds_read_b128 v[124:127], v124 offset:3072
	ds_read_b128 v[136:139], v170
	ds_read_b128 v[148:151], v170 offset:1024
	ds_read_b128 v[152:155], v170 offset:2048
	ds_read_b128 v[170:173], v170 offset:3072
	s_add_u32 s20, s20, s0
	s_addc_u32 s21, s21, 0
	s_mov_b32 m0, s63
	v_lshl_add_u64 v[222:223], s[20:21], 0, v[160:161]
	ds_read_b128 v[174:177], v211 offset:32768
	ds_read_b128 v[178:181], v211 offset:33792
	ds_read_b128 v[182:185], v211 offset:34816
	ds_read_b128 v[186:189], v211 offset:35840
	ds_read_b128 v[190:193], v211 offset:36864
	ds_read_b128 v[194:197], v211 offset:37888
	ds_read_b128 v[198:201], v211 offset:38912
	ds_read_b128 v[202:205], v211 offset:39936
	global_load_lds_dwordx4 v[222:223], off
	v_lshl_add_u64 v[222:223], s[20:21], 0, v[158:159]
	s_mov_b32 m0, s64
	s_nop 0
	global_load_lds_dwordx4 v[222:223], off
	s_waitcnt vmcnt(8)
	s_waitcnt lgkmcnt(0)
	s_setprio 1
	s_barrier
	v_mfma_f32_16x16x32_bf16 v[144:147], v[88:91], v[174:177], v[144:147]
	v_mfma_f32_16x16x32_bf16 v[140:143], v[112:115], v[174:177], v[140:143]
	v_mfma_f32_16x16x32_bf16 v[144:147], v[100:103], v[178:181], v[144:147]
	v_mfma_f32_16x16x32_bf16 v[140:143], v[124:127], v[178:181], v[140:143]
	v_mfma_f32_16x16x32_bf16 v[120:123], v[88:91], v[182:185], v[120:123]
	v_mfma_f32_16x16x32_bf16 v[116:119], v[112:115], v[182:185], v[116:119]
	v_mfma_f32_16x16x32_bf16 v[120:123], v[100:103], v[186:189], v[120:123]
	v_mfma_f32_16x16x32_bf16 v[116:119], v[124:127], v[186:189], v[116:119]
	v_mfma_f32_16x16x32_bf16 v[96:99], v[88:91], v[190:193], v[96:99]
	v_mfma_f32_16x16x32_bf16 v[92:95], v[112:115], v[190:193], v[92:95]
	v_mfma_f32_16x16x32_bf16 v[96:99], v[100:103], v[194:197], v[96:99]
	v_mfma_f32_16x16x32_bf16 v[92:95], v[124:127], v[194:197], v[92:95]
	v_mfma_f32_16x16x32_bf16 v[76:79], v[88:91], v[198:201], v[76:79]
	v_mfma_f32_16x16x32_bf16 v[72:75], v[112:115], v[198:201], v[72:75]
	v_mfma_f32_16x16x32_bf16 v[76:79], v[100:103], v[202:205], v[76:79]
	v_mfma_f32_16x16x32_bf16 v[72:75], v[124:127], v[202:205], v[72:75]
	v_mfma_f32_16x16x32_bf16 v[132:135], v[136:139], v[174:177], v[132:135]
	v_mfma_f32_16x16x32_bf16 v[128:131], v[152:155], v[174:177], v[128:131]
	v_mfma_f32_16x16x32_bf16 v[132:135], v[148:151], v[178:181], v[132:135]
	v_mfma_f32_16x16x32_bf16 v[128:131], v[170:173], v[178:181], v[128:131]
	v_mfma_f32_16x16x32_bf16 v[108:111], v[136:139], v[182:185], v[108:111]
	v_mfma_f32_16x16x32_bf16 v[104:107], v[152:155], v[182:185], v[104:107]
	v_mfma_f32_16x16x32_bf16 v[108:111], v[148:151], v[186:189], v[108:111]
	v_mfma_f32_16x16x32_bf16 v[104:107], v[170:173], v[186:189], v[104:107]
	v_mfma_f32_16x16x32_bf16 v[84:87], v[136:139], v[190:193], v[84:87]
	v_mfma_f32_16x16x32_bf16 v[80:83], v[152:155], v[190:193], v[80:83]
	v_mfma_f32_16x16x32_bf16 v[84:87], v[148:151], v[194:197], v[84:87]
	v_mfma_f32_16x16x32_bf16 v[80:83], v[170:173], v[194:197], v[80:83]
	v_mfma_f32_16x16x32_bf16 v[68:71], v[136:139], v[198:201], v[68:71]
	v_mfma_f32_16x16x32_bf16 v[64:67], v[152:155], v[198:201], v[64:67]
	v_mfma_f32_16x16x32_bf16 v[68:71], v[148:151], v[202:205], v[68:71]
	v_mfma_f32_16x16x32_bf16 v[64:67], v[170:173], v[202:205], v[64:67]
	s_barrier
	s_setprio 0
	s_add_i32 s20, s55, s56
	v_lshl_add_u64 v[166:167], v[166:167], 0, s[36:37]
	s_mov_b32 m0, s20
	ds_read_b128 v[174:177], v211 offset:49152
	ds_read_b128 v[178:181], v211 offset:50176
	ds_read_b128 v[182:185], v211 offset:51200
	ds_read_b128 v[186:189], v211 offset:52224
	ds_read_b128 v[190:193], v211 offset:53248
	ds_read_b128 v[194:197], v211 offset:54272
	ds_read_b128 v[198:201], v211 offset:55296
	ds_read_b128 v[202:205], v211 offset:56320
	global_load_lds_dwordx4 v[166:167], off
	v_lshl_add_u64 v[166:167], v[212:213], 0, s[36:37]
	s_add_i32 m0, s20, 0x2000
	s_add_i32 s20, s72, s56
	global_load_lds_dwordx4 v[166:167], off
	v_lshl_add_u64 v[166:167], v[214:215], 0, s[36:37]
	s_mov_b32 m0, s20
	s_nop 0
	global_load_lds_dwordx4 v[166:167], off
	v_lshl_add_u64 v[166:167], v[216:217], 0, s[36:37]
	s_add_i32 m0, s20, 0x2000
	s_nop 0
	global_load_lds_dwordx4 v[166:167], off
	v_lshl_add_u64 v[166:167], v[218:219], 0, s[36:37]
	s_mov_b32 m0, s66
	s_nop 0
	global_load_lds_dwordx4 v[166:167], off
	v_lshl_add_u64 v[166:167], v[220:221], 0, s[36:37]
	s_mov_b32 m0, s67
	s_nop 0
	global_load_lds_dwordx4 v[166:167], off
	s_waitcnt vmcnt(8)
	s_waitcnt lgkmcnt(0)
	s_setprio 1
	s_barrier
	v_mfma_f32_16x16x32_bf16 v[60:63], v[88:91], v[174:177], v[60:63]
	v_mfma_f32_16x16x32_bf16 v[56:59], v[112:115], v[174:177], v[56:59]
	v_mfma_f32_16x16x32_bf16 v[60:63], v[100:103], v[178:181], v[60:63]
	v_mfma_f32_16x16x32_bf16 v[56:59], v[124:127], v[178:181], v[56:59]
	v_mfma_f32_16x16x32_bf16 v[44:47], v[88:91], v[182:185], v[44:47]
	v_mfma_f32_16x16x32_bf16 v[40:43], v[112:115], v[182:185], v[40:43]
	v_mfma_f32_16x16x32_bf16 v[44:47], v[100:103], v[186:189], v[44:47]
	v_mfma_f32_16x16x32_bf16 v[40:43], v[124:127], v[186:189], v[40:43]
	v_mfma_f32_16x16x32_bf16 v[28:31], v[88:91], v[190:193], v[28:31]
	v_mfma_f32_16x16x32_bf16 v[24:27], v[112:115], v[190:193], v[24:27]
	v_mfma_f32_16x16x32_bf16 v[28:31], v[100:103], v[194:197], v[28:31]
	v_mfma_f32_16x16x32_bf16 v[24:27], v[124:127], v[194:197], v[24:27]
	v_mfma_f32_16x16x32_bf16 v[12:15], v[88:91], v[198:201], v[12:15]
	v_mfma_f32_16x16x32_bf16 v[8:11], v[112:115], v[198:201], v[8:11]
	v_mfma_f32_16x16x32_bf16 v[12:15], v[100:103], v[202:205], v[12:15]
	v_mfma_f32_16x16x32_bf16 v[8:11], v[124:127], v[202:205], v[8:11]
	v_mfma_f32_16x16x32_bf16 v[52:55], v[136:139], v[174:177], v[52:55]
	v_mfma_f32_16x16x32_bf16 v[48:51], v[152:155], v[174:177], v[48:51]
	v_mfma_f32_16x16x32_bf16 v[52:55], v[148:151], v[178:181], v[52:55]
	v_mfma_f32_16x16x32_bf16 v[48:51], v[170:173], v[178:181], v[48:51]
	v_mfma_f32_16x16x32_bf16 v[36:39], v[136:139], v[182:185], v[36:39]
	v_mfma_f32_16x16x32_bf16 v[32:35], v[152:155], v[182:185], v[32:35]
	v_mfma_f32_16x16x32_bf16 v[36:39], v[148:151], v[186:189], v[36:39]
	v_mfma_f32_16x16x32_bf16 v[32:35], v[170:173], v[186:189], v[32:35]
	v_mfma_f32_16x16x32_bf16 v[20:23], v[136:139], v[190:193], v[20:23]
	v_mfma_f32_16x16x32_bf16 v[16:19], v[152:155], v[190:193], v[16:19]
	v_mfma_f32_16x16x32_bf16 v[20:23], v[148:151], v[194:197], v[20:23]
	v_mfma_f32_16x16x32_bf16 v[16:19], v[170:173], v[194:197], v[16:19]
	v_mfma_f32_16x16x32_bf16 v[4:7], v[136:139], v[198:201], v[4:7]
	v_mfma_f32_16x16x32_bf16 v[0:3], v[152:155], v[198:201], v[0:3]
	v_mfma_f32_16x16x32_bf16 v[4:7], v[148:151], v[202:205], v[4:7]
	v_mfma_f32_16x16x32_bf16 v[0:3], v[170:173], v[202:205], v[0:3]
	s_barrier
	s_setprio 0
	s_add_u32 s44, s44, 0x100
	s_addc_u32 s45, s45, 0
	s_add_u32 s42, s42, 0x100
	s_addc_u32 s43, s43, 0
	s_cmp_ge_u32 s54, s3
	s_mov_b32 s20, s54
	s_cbranch_scc0 .LBB0_575
	s_and_b64 vcc, exec, s[16:17]
	s_cbranch_vccz .LBB0_578
	s_barrier

.LBB0_692:
	s_add_u32 s20, s40, 0xfffc0080
	s_addc_u32 s21, s41, -1
	s_add_i32 s71, 0, 0x10000
	s_cmp_eq_u32 s70, 12
	s_cselect_b32 s51, s43, s21
	s_cselect_b32 s50, s66, s20
	s_cselect_b32 s21, s19, s69
	s_cselect_b32 s20, s67, s68
	s_add_i32 s74, 0, 0x14000
	v_add_u32_e32 v150, s71, v156
	v_add_u32_e32 v188, s74, v156
	ds_read_b128 v[138:141], v150
	ds_read_b128 v[142:145], v150 offset:1024
	ds_read_b128 v[146:149], v150 offset:2048
	ds_read_b128 v[150:153], v150 offset:3072
	ds_read_b128 v[176:179], v188
	ds_read_b128 v[180:183], v188 offset:1024
	ds_read_b128 v[184:187], v188 offset:2048
	ds_read_b128 v[188:191], v188 offset:3072
	v_lshl_add_u64 v[224:225], s[40:41], 0, v[136:137]
	s_add_i32 m0, s57, 0xc000
	ds_read_b128 v[192:195], v175
	ds_read_b128 v[196:199], v175 offset:1024
	ds_read_b128 v[200:203], v175 offset:2048
	ds_read_b128 v[204:207], v175 offset:3072
	ds_read_b128 v[208:211], v175 offset:4096
	ds_read_b128 v[212:215], v175 offset:5120
	ds_read_b128 v[216:219], v175 offset:6144
	ds_read_b128 v[220:223], v175 offset:7168
	global_load_lds_dwordx4 v[224:225], off
	v_lshl_add_u64 v[224:225], s[40:41], 0, v[134:135]
	s_add_i32 m0, s57, 0xe000
	s_nop 0
	global_load_lds_dwordx4 v[224:225], off
	s_waitcnt vmcnt(8)
	s_waitcnt lgkmcnt(0)
	s_setprio 1
	s_barrier
	v_mfma_f32_16x16x32_bf16 v[124:127], v[138:141], v[192:195], v[124:127]
	v_mfma_f32_16x16x32_bf16 v[112:115], v[146:149], v[192:195], v[112:115]
	v_mfma_f32_16x16x32_bf16 v[124:127], v[142:145], v[196:199], v[124:127]
	v_mfma_f32_16x16x32_bf16 v[112:115], v[150:153], v[196:199], v[112:115]
	v_mfma_f32_16x16x32_bf16 v[108:111], v[138:141], v[200:203], v[108:111]
	v_mfma_f32_16x16x32_bf16 v[96:99], v[146:149], v[200:203], v[96:99]
	v_mfma_f32_16x16x32_bf16 v[108:111], v[142:145], v[204:207], v[108:111]
	v_mfma_f32_16x16x32_bf16 v[96:99], v[150:153], v[204:207], v[96:99]
	v_mfma_f32_16x16x32_bf16 v[92:95], v[138:141], v[208:211], v[92:95]
	v_mfma_f32_16x16x32_bf16 v[80:83], v[146:149], v[208:211], v[80:83]
	v_mfma_f32_16x16x32_bf16 v[92:95], v[142:145], v[212:215], v[92:95]
	v_mfma_f32_16x16x32_bf16 v[80:83], v[150:153], v[212:215], v[80:83]
	v_mfma_f32_16x16x32_bf16 v[76:79], v[138:141], v[216:219], v[76:79]
	v_mfma_f32_16x16x32_bf16 v[64:67], v[146:149], v[216:219], v[64:67]
	v_mfma_f32_16x16x32_bf16 v[76:79], v[142:145], v[220:223], v[76:79]
	v_mfma_f32_16x16x32_bf16 v[64:67], v[150:153], v[220:223], v[64:67]
	v_mfma_f32_16x16x32_bf16 v[120:123], v[176:179], v[192:195], v[120:123]
	v_mfma_f32_16x16x32_bf16 v[116:119], v[184:187], v[192:195], v[116:119]
	v_mfma_f32_16x16x32_bf16 v[120:123], v[180:183], v[196:199], v[120:123]
	v_mfma_f32_16x16x32_bf16 v[116:119], v[188:191], v[196:199], v[116:119]
	v_mfma_f32_16x16x32_bf16 v[104:107], v[176:179], v[200:203], v[104:107]
	v_mfma_f32_16x16x32_bf16 v[100:103], v[184:187], v[200:203], v[100:103]
	v_mfma_f32_16x16x32_bf16 v[104:107], v[180:183], v[204:207], v[104:107]
	v_mfma_f32_16x16x32_bf16 v[100:103], v[188:191], v[204:207], v[100:103]
	v_mfma_f32_16x16x32_bf16 v[88:91], v[176:179], v[208:211], v[88:91]
	v_mfma_f32_16x16x32_bf16 v[84:87], v[184:187], v[208:211], v[84:87]
	v_mfma_f32_16x16x32_bf16 v[88:91], v[180:183], v[212:215], v[88:91]
	v_mfma_f32_16x16x32_bf16 v[84:87], v[188:191], v[212:215], v[84:87]
	v_mfma_f32_16x16x32_bf16 v[72:75], v[176:179], v[216:219], v[72:75]
	v_mfma_f32_16x16x32_bf16 v[68:71], v[184:187], v[216:219], v[68:71]
	v_mfma_f32_16x16x32_bf16 v[72:75], v[180:183], v[220:223], v[72:75]
	v_mfma_f32_16x16x32_bf16 v[68:71], v[188:191], v[220:223], v[68:71]
	s_barrier
	s_setprio 0
	s_add_i32 s71, s71, s54
	v_lshl_add_u64 v[224:225], s[20:21], 0, v[168:169]
	s_mov_b32 m0, s71
	ds_read_b128 v[192:195], v175 offset:16384
	ds_read_b128 v[196:199], v175 offset:17408
	ds_read_b128 v[200:203], v175 offset:18432
	ds_read_b128 v[204:207], v175 offset:19456
	ds_read_b128 v[208:211], v175 offset:20480
	ds_read_b128 v[212:215], v175 offset:21504
	ds_read_b128 v[216:219], v175 offset:22528
	ds_read_b128 v[220:223], v175 offset:23552
	global_load_lds_dwordx4 v[224:225], off
	s_add_i32 m0, s71, 0x2000
	s_add_u32 s72, s20, 0x40000
	v_lshl_add_u64 v[226:227], s[20:21], 0, v[128:129]
	s_addc_u32 s73, s21, 0
	s_add_i32 s71, s74, s54
	global_load_lds_dwordx4 v[226:227], off
	v_lshl_add_u64 v[228:229], s[72:73], 0, v[168:169]
	s_mov_b32 m0, s71
	v_lshl_add_u64 v[230:231], s[50:51], 0, v[130:131]
	global_load_lds_dwordx4 v[228:229], off
	v_lshl_add_u64 v[228:229], s[72:73], 0, v[128:129]
	s_add_i32 m0, s71, 0x2000
	s_nop 0
	global_load_lds_dwordx4 v[228:229], off
	v_lshl_add_u64 v[228:229], s[50:51], 0, v[132:133]
	s_mov_b32 m0, s57
	s_nop 0
	global_load_lds_dwordx4 v[228:229], off
	s_mov_b32 m0, s58
	s_nop 0
	global_load_lds_dwordx4 v[230:231], off
	s_waitcnt vmcnt(8)
	s_waitcnt lgkmcnt(0)
	s_setprio 1
	s_barrier
	v_mfma_f32_16x16x32_bf16 v[60:63], v[138:141], v[192:195], v[60:63]
	v_mfma_f32_16x16x32_bf16 v[48:51], v[146:149], v[192:195], v[48:51]
	v_mfma_f32_16x16x32_bf16 v[60:63], v[142:145], v[196:199], v[60:63]
	v_mfma_f32_16x16x32_bf16 v[48:51], v[150:153], v[196:199], v[48:51]
	v_mfma_f32_16x16x32_bf16 v[44:47], v[138:141], v[200:203], v[44:47]
	v_mfma_f32_16x16x32_bf16 v[32:35], v[146:149], v[200:203], v[32:35]
	v_mfma_f32_16x16x32_bf16 v[44:47], v[142:145], v[204:207], v[44:47]
	v_mfma_f32_16x16x32_bf16 v[32:35], v[150:153], v[204:207], v[32:35]
	v_mfma_f32_16x16x32_bf16 v[28:31], v[138:141], v[208:211], v[28:31]
	v_mfma_f32_16x16x32_bf16 v[16:19], v[146:149], v[208:211], v[16:19]
	v_mfma_f32_16x16x32_bf16 v[28:31], v[142:145], v[212:215], v[28:31]
	v_mfma_f32_16x16x32_bf16 v[16:19], v[150:153], v[212:215], v[16:19]
	v_mfma_f32_16x16x32_bf16 v[12:15], v[138:141], v[216:219], v[12:15]
	v_mfma_f32_16x16x32_bf16 v[4:7], v[146:149], v[216:219], v[4:7]
	v_mfma_f32_16x16x32_bf16 v[12:15], v[142:145], v[220:223], v[12:15]
	v_mfma_f32_16x16x32_bf16 v[4:7], v[150:153], v[220:223], v[4:7]
	v_mfma_f32_16x16x32_bf16 v[56:59], v[176:179], v[192:195], v[56:59]
	v_mfma_f32_16x16x32_bf16 v[52:55], v[184:187], v[192:195], v[52:55]
	v_mfma_f32_16x16x32_bf16 v[56:59], v[180:183], v[196:199], v[56:59]
	v_mfma_f32_16x16x32_bf16 v[52:55], v[188:191], v[196:199], v[52:55]
	v_mfma_f32_16x16x32_bf16 v[40:43], v[176:179], v[200:203], v[40:43]
	v_mfma_f32_16x16x32_bf16 v[36:39], v[184:187], v[200:203], v[36:39]
	v_mfma_f32_16x16x32_bf16 v[40:43], v[180:183], v[204:207], v[40:43]
	v_mfma_f32_16x16x32_bf16 v[36:39], v[188:191], v[204:207], v[36:39]
	v_mfma_f32_16x16x32_bf16 v[24:27], v[176:179], v[208:211], v[24:27]
	v_mfma_f32_16x16x32_bf16 v[20:23], v[184:187], v[208:211], v[20:23]
	v_mfma_f32_16x16x32_bf16 v[24:27], v[180:183], v[212:215], v[24:27]
	v_mfma_f32_16x16x32_bf16 v[20:23], v[188:191], v[212:215], v[20:23]
	v_mfma_f32_16x16x32_bf16 v[8:11], v[176:179], v[216:219], v[8:11]
	v_mfma_f32_16x16x32_bf16 v[0:3], v[184:187], v[216:219], v[0:3]
	v_mfma_f32_16x16x32_bf16 v[8:11], v[180:183], v[220:223], v[8:11]
	v_mfma_f32_16x16x32_bf16 v[0:3], v[188:191], v[220:223], v[0:3]
	s_barrier
	s_setprio 0
	s_add_i32 s71, 0, 0x18000
	s_add_i32 s72, 0, 0x1c000
	v_add_u32_e32 v150, s71, v156
	v_add_u32_e32 v188, s72, v156
	ds_read_b128 v[138:141], v150
	ds_read_b128 v[142:145], v150 offset:1024
	ds_read_b128 v[146:149], v150 offset:2048
	ds_read_b128 v[150:153], v150 offset:3072
	ds_read_b128 v[176:179], v188
	ds_read_b128 v[180:183], v188 offset:1024
	ds_read_b128 v[184:187], v188 offset:2048
	ds_read_b128 v[188:191], v188 offset:3072
	s_add_u32 s50, s50, 0x40000
	s_addc_u32 s51, s51, 0
	s_mov_b32 m0, s59
	v_lshl_add_u64 v[232:233], s[50:51], 0, v[132:133]
	ds_read_b128 v[192:195], v175 offset:32768
	ds_read_b128 v[196:199], v175 offset:33792
	ds_read_b128 v[200:203], v175 offset:34816
	ds_read_b128 v[204:207], v175 offset:35840
	ds_read_b128 v[208:211], v175 offset:36864
	ds_read_b128 v[212:215], v175 offset:37888
	ds_read_b128 v[216:219], v175 offset:38912
	ds_read_b128 v[220:223], v175 offset:39936
	global_load_lds_dwordx4 v[232:233], off
	v_lshl_add_u64 v[232:233], s[50:51], 0, v[130:131]
	s_mov_b32 m0, s60
	s_nop 0
	global_load_lds_dwordx4 v[232:233], off
	s_waitcnt vmcnt(8)
	s_waitcnt lgkmcnt(0)
	s_setprio 1
	s_barrier
	v_mfma_f32_16x16x32_bf16 v[124:127], v[138:141], v[192:195], v[124:127]
	v_mfma_f32_16x16x32_bf16 v[112:115], v[146:149], v[192:195], v[112:115]
	v_mfma_f32_16x16x32_bf16 v[124:127], v[142:145], v[196:199], v[124:127]
	v_mfma_f32_16x16x32_bf16 v[112:115], v[150:153], v[196:199], v[112:115]
	v_mfma_f32_16x16x32_bf16 v[108:111], v[138:141], v[200:203], v[108:111]
	v_mfma_f32_16x16x32_bf16 v[96:99], v[146:149], v[200:203], v[96:99]
	v_mfma_f32_16x16x32_bf16 v[108:111], v[142:145], v[204:207], v[108:111]
	v_mfma_f32_16x16x32_bf16 v[96:99], v[150:153], v[204:207], v[96:99]
	v_mfma_f32_16x16x32_bf16 v[92:95], v[138:141], v[208:211], v[92:95]
	v_mfma_f32_16x16x32_bf16 v[80:83], v[146:149], v[208:211], v[80:83]
	v_mfma_f32_16x16x32_bf16 v[92:95], v[142:145], v[212:215], v[92:95]
	v_mfma_f32_16x16x32_bf16 v[80:83], v[150:153], v[212:215], v[80:83]
	v_mfma_f32_16x16x32_bf16 v[76:79], v[138:141], v[216:219], v[76:79]
	v_mfma_f32_16x16x32_bf16 v[64:67], v[146:149], v[216:219], v[64:67]
	v_mfma_f32_16x16x32_bf16 v[76:79], v[142:145], v[220:223], v[76:79]
	v_mfma_f32_16x16x32_bf16 v[64:67], v[150:153], v[220:223], v[64:67]
	v_mfma_f32_16x16x32_bf16 v[120:123], v[176:179], v[192:195], v[120:123]
	v_mfma_f32_16x16x32_bf16 v[116:119], v[184:187], v[192:195], v[116:119]
	v_mfma_f32_16x16x32_bf16 v[120:123], v[180:183], v[196:199], v[120:123]
	v_mfma_f32_16x16x32_bf16 v[116:119], v[188:191], v[196:199], v[116:119]
	v_mfma_f32_16x16x32_bf16 v[104:107], v[176:179], v[200:203], v[104:107]
	v_mfma_f32_16x16x32_bf16 v[100:103], v[184:187], v[200:203], v[100:103]
	v_mfma_f32_16x16x32_bf16 v[104:107], v[180:183], v[204:207], v[104:107]
	v_mfma_f32_16x16x32_bf16 v[100:103], v[188:191], v[204:207], v[100:103]
	v_mfma_f32_16x16x32_bf16 v[88:91], v[176:179], v[208:211], v[88:91]
	v_mfma_f32_16x16x32_bf16 v[84:87], v[184:187], v[208:211], v[84:87]
	v_mfma_f32_16x16x32_bf16 v[88:91], v[180:183], v[212:215], v[88:91]
	v_mfma_f32_16x16x32_bf16 v[84:87], v[188:191], v[212:215], v[84:87]
	v_mfma_f32_16x16x32_bf16 v[72:75], v[176:179], v[216:219], v[72:75]
	v_mfma_f32_16x16x32_bf16 v[68:71], v[184:187], v[216:219], v[68:71]
	v_mfma_f32_16x16x32_bf16 v[72:75], v[180:183], v[220:223], v[72:75]
	v_mfma_f32_16x16x32_bf16 v[68:71], v[188:191], v[220:223], v[68:71]
	s_barrier
	s_setprio 0
	s_add_i32 s50, s71, s54
	v_lshl_add_u64 v[224:225], v[224:225], 0, s[36:37]
	s_mov_b32 m0, s50
	ds_read_b128 v[192:195], v175 offset:49152
	ds_read_b128 v[196:199], v175 offset:50176
	ds_read_b128 v[200:203], v175 offset:51200
	ds_read_b128 v[204:207], v175 offset:52224
	ds_read_b128 v[208:211], v175 offset:53248
	ds_read_b128 v[212:215], v175 offset:54272
	ds_read_b128 v[216:219], v175 offset:55296
	ds_read_b128 v[220:223], v175 offset:56320
	global_load_lds_dwordx4 v[224:225], off
	s_add_i32 m0, s50, 0x2000
	s_add_u32 s20, s20, 0x40080
	v_lshl_add_u64 v[224:225], v[226:227], 0, s[36:37]
	s_addc_u32 s21, s21, 0
	s_add_i32 s50, s72, s54
	global_load_lds_dwordx4 v[224:225], off
	v_lshl_add_u64 v[224:225], s[20:21], 0, v[168:169]
	s_mov_b32 m0, s50
	s_nop 0
	global_load_lds_dwordx4 v[224:225], off
	v_lshl_add_u64 v[224:225], s[20:21], 0, v[128:129]
	s_add_i32 m0, s50, 0x2000
	s_nop 0
	global_load_lds_dwordx4 v[224:225], off
	v_lshl_add_u64 v[224:225], v[228:229], 0, s[36:37]
	s_mov_b32 m0, s61
	s_nop 0
	global_load_lds_dwordx4 v[224:225], off
	v_lshl_add_u64 v[224:225], v[230:231], 0, s[36:37]
	s_mov_b32 m0, s62
	s_nop 0
	global_load_lds_dwordx4 v[224:225], off
	s_waitcnt vmcnt(8)
	s_waitcnt lgkmcnt(0)
	s_setprio 1
	s_barrier
	v_mfma_f32_16x16x32_bf16 v[60:63], v[138:141], v[192:195], v[60:63]
	v_mfma_f32_16x16x32_bf16 v[48:51], v[146:149], v[192:195], v[48:51]
	v_mfma_f32_16x16x32_bf16 v[60:63], v[142:145], v[196:199], v[60:63]
	v_mfma_f32_16x16x32_bf16 v[48:51], v[150:153], v[196:199], v[48:51]
	v_mfma_f32_16x16x32_bf16 v[44:47], v[138:141], v[200:203], v[44:47]
	v_mfma_f32_16x16x32_bf16 v[32:35], v[146:149], v[200:203], v[32:35]
	v_mfma_f32_16x16x32_bf16 v[44:47], v[142:145], v[204:207], v[44:47]
	v_mfma_f32_16x16x32_bf16 v[32:35], v[150:153], v[204:207], v[32:35]
	v_mfma_f32_16x16x32_bf16 v[28:31], v[138:141], v[208:211], v[28:31]
	v_mfma_f32_16x16x32_bf16 v[16:19], v[146:149], v[208:211], v[16:19]
	v_mfma_f32_16x16x32_bf16 v[28:31], v[142:145], v[212:215], v[28:31]
	v_mfma_f32_16x16x32_bf16 v[16:19], v[150:153], v[212:215], v[16:19]
	v_mfma_f32_16x16x32_bf16 v[12:15], v[138:141], v[216:219], v[12:15]
	v_mfma_f32_16x16x32_bf16 v[4:7], v[146:149], v[216:219], v[4:7]
	v_mfma_f32_16x16x32_bf16 v[12:15], v[142:145], v[220:223], v[12:15]
	v_mfma_f32_16x16x32_bf16 v[4:7], v[150:153], v[220:223], v[4:7]
	v_mfma_f32_16x16x32_bf16 v[56:59], v[176:179], v[192:195], v[56:59]
	v_mfma_f32_16x16x32_bf16 v[52:55], v[184:187], v[192:195], v[52:55]
	v_mfma_f32_16x16x32_bf16 v[56:59], v[180:183], v[196:199], v[56:59]
	v_mfma_f32_16x16x32_bf16 v[52:55], v[188:191], v[196:199], v[52:55]
	v_mfma_f32_16x16x32_bf16 v[40:43], v[176:179], v[200:203], v[40:43]
	v_mfma_f32_16x16x32_bf16 v[36:39], v[184:187], v[200:203], v[36:39]
	v_mfma_f32_16x16x32_bf16 v[40:43], v[180:183], v[204:207], v[40:43]
	v_mfma_f32_16x16x32_bf16 v[36:39], v[188:191], v[204:207], v[36:39]
	v_mfma_f32_16x16x32_bf16 v[24:27], v[176:179], v[208:211], v[24:27]
	v_mfma_f32_16x16x32_bf16 v[20:23], v[184:187], v[208:211], v[20:23]
	v_mfma_f32_16x16x32_bf16 v[24:27], v[180:183], v[212:215], v[24:27]
	v_mfma_f32_16x16x32_bf16 v[20:23], v[188:191], v[212:215], v[20:23]
	v_mfma_f32_16x16x32_bf16 v[8:11], v[176:179], v[216:219], v[8:11]
	v_mfma_f32_16x16x32_bf16 v[0:3], v[184:187], v[216:219], v[0:3]
	v_mfma_f32_16x16x32_bf16 v[8:11], v[180:183], v[220:223], v[8:11]
	v_mfma_f32_16x16x32_bf16 v[0:3], v[188:191], v[220:223], v[0:3]
	s_barrier
	s_setprio 0
	s_add_i32 s70, s70, 2
	s_add_u32 s68, s68, 0x100
	s_addc_u32 s69, s69, 0
	s_add_u32 s40, s40, 0x100
	s_addc_u32 s41, s41, 0
	s_cmp_gt_u32 s70, 13
	s_cbranch_scc0 .LBB0_692
	s_and_b64 vcc, exec, s[16:17]
	s_cbranch_vccz .LBB0_695
	s_barrier
